# grid barrier: agent acquire (buffer_inv sc1) issued at arrival (leader: after its L2 write-back, before cross-XCD arrival) instead of after the release, so it completes during the wait
# speedup vs baseline: 1.0077x; 1.0077x over previous
.LBB0_692:
	s_or_b64 exec, exec, s[12:13]
	v_cvt_f32_u32_e32 v5, v3
	s_waitcnt vmcnt(0)
	v_readfirstlane_b32 s2, v4
	v_sub_u32_e32 v4, 0, v3
	v_rcp_iflag_f32_e32 v5, v5
	v_add_u32_e32 v6, s2, v2
	v_mul_f32_e32 v5, 0x4f7ffffe, v5
	v_cvt_u32_f32_e32 v5, v5
	v_mul_lo_u32 v2, v4, v5
	v_mul_hi_u32 v2, v5, v2
	v_add_u32_e32 v2, v5, v2
	v_mul_hi_u32 v2, v6, v2
	v_mul_lo_u32 v4, v2, v3
	v_sub_u32_e32 v4, v6, v4
	v_add_u32_e32 v5, 1, v2
	v_cmp_ge_u32_e32 vcc, v4, v3
	s_nop 1
	v_cndmask_b32_e32 v2, v2, v5, vcc
	v_sub_u32_e32 v5, v4, v3
	v_cndmask_b32_e32 v4, v4, v5, vcc
	v_add_u32_e32 v5, 1, v2
	v_cmp_ge_u32_e32 vcc, v4, v3
	v_add_u32_e32 v4, 1, v6
	s_nop 0
	v_cndmask_b32_e32 v2, v2, v5, vcc
	v_mul_lo_u32 v5, v3, v2
	v_add_u32_e32 v3, v5, v3
	v_cmp_ne_u32_e32 vcc, v4, v3
	s_and_saveexec_b64 s[2:3], vcc
	s_xor_b64 s[10:11], exec, s[2:3]
	s_cbranch_execz .LBB0_706
	s_waitcnt lgkmcnt(0)
	v_mov_b32_e32 v1, 0x2000
	buffer_inv sc1
	global_load_dword v1, v1, s[8:9] offset:1024 sc1
	s_add_u32 s16, s8, 0x2400
	s_addc_u32 s17, s9, 0
	s_waitcnt vmcnt(0)
	v_cmp_eq_u32_e32 vcc, v1, v2
	s_and_saveexec_b64 s[12:13], vcc
	s_cbranch_execz .LBB0_705
	s_add_u32 s14, s94, 0x4200
	s_addc_u32 s15, s95, 0
	s_mov_b32 s2, 1
	s_mov_b64 s[18:19], 0
	v_mov_b32_e32 v1, 0
	s_branch .LBB0_696

.LBB0_705:
	s_or_b64 exec, exec, s[12:13]
	s_waitcnt vmcnt(0)
	s_waitcnt vmcnt(0)
.LBB0_706:
	s_andn2_saveexec_b64 s[2:3], s[10:11]
	s_cbranch_execz .LBB0_726
	s_mov_b64 s[10:11], exec
	buffer_wbl2 sc1
	s_waitcnt lgkmcnt(0)
	s_waitcnt vmcnt(0)
	buffer_inv sc1
	v_mbcnt_lo_u32_b32 v2, s10, 0
	v_mbcnt_hi_u32_b32 v2, s11, v2
	v_cmp_eq_u32_e32 vcc, 0, v2
	s_and_saveexec_b64 s[12:13], vcc
	s_cbranch_execz .LBB0_709
	s_bcnt1_i32_b64 s2, s[10:11]
	v_mov_b32_e32 v3, 0x7000
	v_mov_b32_e32 v4, s2
	global_atomic_add v3, v3, v4, s[94:95] offset:1024 sc0

.LBB0_723:
	s_or_b64 exec, exec, s[10:11]
	s_mov_b64 s[10:11], exec
	v_mbcnt_lo_u32_b32 v1, s10, 0
	v_mbcnt_hi_u32_b32 v1, s11, v1
	v_cmp_eq_u32_e32 vcc, 0, v1
	s_waitcnt vmcnt(0)
	s_and_saveexec_b64 s[12:13], vcc
	s_cbranch_execz .LBB0_725
	s_bcnt1_i32_b64 s2, s[10:11]
	v_mov_b32_e32 v1, 0x2000
	v_mov_b32_e32 v2, s2
	global_atomic_add v1, v2, s[8:9] offset:1024

.LBB0_754:
	s_or_b64 exec, exec, s[10:11]
	v_cvt_f32_u32_e32 v5, v3
	s_waitcnt vmcnt(0)
	v_readfirstlane_b32 s5, v4
	v_sub_u32_e32 v4, 0, v3
	v_rcp_iflag_f32_e32 v5, v5
	v_add_u32_e32 v6, s5, v2
	v_mul_f32_e32 v5, 0x4f7ffffe, v5
	v_cvt_u32_f32_e32 v5, v5
	v_mul_lo_u32 v2, v4, v5
	v_mul_hi_u32 v2, v5, v2
	v_add_u32_e32 v2, v5, v2
	v_mul_hi_u32 v2, v6, v2
	v_mul_lo_u32 v4, v2, v3
	v_sub_u32_e32 v4, v6, v4
	v_add_u32_e32 v5, 1, v2
	v_cmp_ge_u32_e32 vcc, v4, v3
	s_nop 1
	v_cndmask_b32_e32 v2, v2, v5, vcc
	v_sub_u32_e32 v5, v4, v3
	v_cndmask_b32_e32 v4, v4, v5, vcc
	v_add_u32_e32 v5, 1, v2
	v_cmp_ge_u32_e32 vcc, v4, v3
	v_add_u32_e32 v4, 1, v6
	s_nop 0
	v_cndmask_b32_e32 v2, v2, v5, vcc
	v_mul_lo_u32 v5, v3, v2
	v_add_u32_e32 v3, v5, v3
	v_cmp_ne_u32_e32 vcc, v4, v3
	s_and_saveexec_b64 s[8:9], vcc
	s_xor_b64 s[8:9], exec, s[8:9]
	s_cbranch_execz .LBB0_768
	s_add_i32 s10, s4, 0x900
	s_mov_b32 s11, 0
	s_lshl_b64 s[10:11], s[10:11], 2
	v_readlane_b32 s5, v228, 8
	s_add_u32 s16, s5, s10
	v_readlane_b32 s5, v228, 10
	s_addc_u32 s17, s5, s11
	s_waitcnt lgkmcnt(0)
	v_mov_b32_e32 v1, 0
	buffer_inv sc1
	global_load_dword v3, v1, s[16:17] sc1
	s_waitcnt vmcnt(0)
	v_cmp_eq_u32_e32 vcc, v3, v2
	s_and_saveexec_b64 s[10:11], vcc
	s_cbranch_execz .LBB0_767
	s_add_u32 s14, s38, 0x4200
	s_addc_u32 s15, s39, 0
	s_mov_b32 s5, 1
	s_mov_b64 s[18:19], 0
	s_branch .LBB0_758

.LBB0_767:
	s_or_b64 exec, exec, s[10:11]
	s_waitcnt vmcnt(0)
	s_waitcnt vmcnt(0)
.LBB0_768:
	s_andn2_saveexec_b64 s[8:9], s[8:9]
	s_cbranch_execz .LBB0_788
	s_mov_b64 s[8:9], exec
	buffer_wbl2 sc1
	s_waitcnt lgkmcnt(0)
	s_waitcnt vmcnt(0)
	buffer_inv sc1
	v_mbcnt_lo_u32_b32 v2, s8, 0
	v_mbcnt_hi_u32_b32 v2, s9, v2
	v_cmp_eq_u32_e32 vcc, 0, v2
	s_and_saveexec_b64 s[10:11], vcc
	s_cbranch_execz .LBB0_771
	s_bcnt1_i32_b64 s5, s[8:9]
	v_mov_b32_e32 v3, 0x7000
	v_mov_b32_e32 v4, s5
	global_atomic_add v3, v3, v4, s[38:39] offset:1024 sc0

.LBB0_785:
	s_or_b64 exec, exec, s[8:9]
	s_mov_b64 s[8:9], exec
	v_mbcnt_lo_u32_b32 v1, s8, 0
	v_mbcnt_hi_u32_b32 v1, s9, v1
	s_mov_b32 s15, 0
	v_cmp_eq_u32_e32 vcc, 0, v1
	s_waitcnt vmcnt(0)
	s_and_saveexec_b64 s[10:11], vcc
	s_cbranch_execz .LBB0_787
	s_add_i32 s14, s4, 0x900
	s_lshl_b64 s[4:5], s[14:15], 2
	v_readlane_b32 s13, v228, 8
	s_add_u32 s4, s13, s4
	v_readlane_b32 s13, v228, 10
	s_addc_u32 s5, s13, s5
	s_bcnt1_i32_b64 s8, s[8:9]
	v_mov_b32_e32 v1, 0
	v_mov_b32_e32 v2, s8
	global_atomic_add v1, v2, s[4:5]

.LBB0_901:
	s_or_b64 exec, exec, s[14:15]
	v_cvt_f32_u32_e32 v5, v3
	s_waitcnt vmcnt(0)
	v_readfirstlane_b32 s5, v4
	v_sub_u32_e32 v4, 0, v3
	v_rcp_iflag_f32_e32 v5, v5
	v_add_u32_e32 v6, s5, v2
	v_mul_f32_e32 v5, 0x4f7ffffe, v5
	v_cvt_u32_f32_e32 v5, v5
	v_mul_lo_u32 v2, v4, v5
	v_mul_hi_u32 v2, v5, v2
	v_add_u32_e32 v2, v5, v2
	v_mul_hi_u32 v2, v6, v2
	v_mul_lo_u32 v4, v2, v3
	v_sub_u32_e32 v4, v6, v4
	v_add_u32_e32 v5, 1, v2
	v_cmp_ge_u32_e32 vcc, v4, v3
	s_nop 1
	v_cndmask_b32_e32 v2, v2, v5, vcc
	v_sub_u32_e32 v5, v4, v3
	v_cndmask_b32_e32 v4, v4, v5, vcc
	v_add_u32_e32 v5, 1, v2
	v_cmp_ge_u32_e32 vcc, v4, v3
	v_add_u32_e32 v4, 1, v6
	s_nop 0
	v_cndmask_b32_e32 v2, v2, v5, vcc
	v_mul_lo_u32 v5, v3, v2
	v_add_u32_e32 v3, v5, v3
	v_cmp_ne_u32_e32 vcc, v4, v3
	s_and_saveexec_b64 s[10:11], vcc
	s_xor_b64 s[10:11], exec, s[10:11]
	s_cbranch_execz .LBB0_915
	s_add_i32 s14, s4, 0x900
	s_mov_b32 s15, 0
	s_lshl_b64 s[14:15], s[14:15], 2
	v_readlane_b32 s5, v228, 8
	s_add_u32 s18, s5, s14
	v_readlane_b32 s5, v228, 10
	s_addc_u32 s19, s5, s15
	s_waitcnt lgkmcnt(0)
	v_mov_b32_e32 v1, 0
	buffer_inv sc1
	global_load_dword v3, v1, s[18:19] sc1
	s_waitcnt vmcnt(0)
	v_cmp_eq_u32_e32 vcc, v3, v2
	s_and_saveexec_b64 s[14:15], vcc
	s_cbranch_execz .LBB0_914
	s_add_u32 s16, s38, 0x4200
	s_addc_u32 s17, s39, 0
	s_mov_b32 s5, 1
	s_mov_b64 s[20:21], 0
	s_branch .LBB0_905

.LBB0_914:
	s_or_b64 exec, exec, s[14:15]
	s_waitcnt vmcnt(0)
	s_waitcnt vmcnt(0)
.LBB0_915:
	s_andn2_saveexec_b64 s[10:11], s[10:11]
	s_cbranch_execz .LBB0_935
	s_mov_b64 s[10:11], exec
	buffer_wbl2 sc1
	s_waitcnt lgkmcnt(0)
	s_waitcnt vmcnt(0)
	buffer_inv sc1
	v_mbcnt_lo_u32_b32 v2, s10, 0
	v_mbcnt_hi_u32_b32 v2, s11, v2
	v_cmp_eq_u32_e32 vcc, 0, v2
	s_and_saveexec_b64 s[14:15], vcc
	s_cbranch_execz .LBB0_918
	s_bcnt1_i32_b64 s5, s[10:11]
	v_mov_b32_e32 v3, 0x7000
	v_mov_b32_e32 v4, s5
	global_atomic_add v3, v3, v4, s[38:39] offset:1024 sc0

.LBB0_932:
	s_or_b64 exec, exec, s[10:11]
	s_mov_b64 s[10:11], exec
	v_mbcnt_lo_u32_b32 v1, s10, 0
	v_mbcnt_hi_u32_b32 v1, s11, v1
	s_mov_b32 s17, 0
	v_cmp_eq_u32_e32 vcc, 0, v1
	s_waitcnt vmcnt(0)
	s_and_saveexec_b64 s[14:15], vcc
	s_cbranch_execz .LBB0_934
	s_add_i32 s16, s4, 0x900
	s_lshl_b64 s[4:5], s[16:17], 2
	v_readlane_b32 s13, v228, 8
	s_add_u32 s4, s13, s4
	v_readlane_b32 s13, v228, 10
	s_addc_u32 s5, s13, s5
	s_bcnt1_i32_b64 s10, s[10:11]
	v_mov_b32_e32 v1, 0
	v_mov_b32_e32 v2, s10
	global_atomic_add v1, v2, s[4:5]

.LBB0_1024:
	s_or_b64 exec, exec, s[10:11]
	v_cvt_f32_u32_e32 v5, v3
	s_waitcnt vmcnt(0)
	v_readfirstlane_b32 s4, v4
	v_sub_u32_e32 v4, 0, v3
	v_rcp_iflag_f32_e32 v5, v5
	v_add_u32_e32 v6, s4, v2
	v_mul_f32_e32 v5, 0x4f7ffffe, v5
	v_cvt_u32_f32_e32 v5, v5
	v_mul_lo_u32 v2, v4, v5
	v_mul_hi_u32 v2, v5, v2
	v_add_u32_e32 v2, v5, v2
	v_mul_hi_u32 v2, v6, v2
	v_mul_lo_u32 v4, v2, v3
	v_sub_u32_e32 v4, v6, v4
	v_add_u32_e32 v5, 1, v2
	v_cmp_ge_u32_e32 vcc, v4, v3
	s_nop 1
	v_cndmask_b32_e32 v2, v2, v5, vcc
	v_sub_u32_e32 v5, v4, v3
	v_cndmask_b32_e32 v4, v4, v5, vcc
	v_add_u32_e32 v5, 1, v2
	v_cmp_ge_u32_e32 vcc, v4, v3
	v_add_u32_e32 v4, 1, v6
	s_nop 0
	v_cndmask_b32_e32 v2, v2, v5, vcc
	v_mul_lo_u32 v5, v3, v2
	v_add_u32_e32 v3, v5, v3
	v_cmp_ne_u32_e32 vcc, v4, v3
	s_and_saveexec_b64 s[4:5], vcc
	s_xor_b64 s[8:9], exec, s[4:5]
	s_cbranch_execz .LBB0_1038
	s_add_i32 s4, s2, 0x900
	s_mov_b32 s5, 0
	s_lshl_b64 s[4:5], s[4:5], 2
	v_readlane_b32 s10, v228, 8
	s_add_u32 s16, s10, s4
	v_readlane_b32 s4, v228, 10
	s_addc_u32 s17, s4, s5
	s_waitcnt lgkmcnt(0)
	v_mov_b32_e32 v1, 0
	buffer_inv sc1
	global_load_dword v3, v1, s[16:17] sc1
	s_waitcnt vmcnt(0)
	v_cmp_eq_u32_e32 vcc, v3, v2
	s_and_saveexec_b64 s[10:11], vcc
	s_cbranch_execz .LBB0_1037
	s_add_u32 s14, s38, 0x4200
	s_addc_u32 s15, s39, 0
	s_mov_b32 s4, 1
	s_mov_b64 s[18:19], 0
	s_branch .LBB0_1028

.LBB0_1038:
	s_andn2_saveexec_b64 s[4:5], s[8:9]
	s_cbranch_execz .LBB0_1058
	s_mov_b64 s[8:9], exec
	buffer_wbl2 sc1
	s_waitcnt lgkmcnt(0)
	s_waitcnt vmcnt(0)
	buffer_inv sc1
	v_mbcnt_lo_u32_b32 v2, s8, 0
	v_mbcnt_hi_u32_b32 v2, s9, v2
	v_cmp_eq_u32_e32 vcc, 0, v2
	s_and_saveexec_b64 s[10:11], vcc
	s_cbranch_execz .LBB0_1041
	s_bcnt1_i32_b64 s4, s[8:9]
	v_mov_b32_e32 v3, 0x7000
	v_mov_b32_e32 v4, s4
	global_atomic_add v3, v3, v4, s[38:39] offset:1024 sc0

.LBB0_1055:
	s_or_b64 exec, exec, s[8:9]
	s_mov_b64 s[8:9], exec
	v_mbcnt_lo_u32_b32 v1, s8, 0
	v_mbcnt_hi_u32_b32 v1, s9, v1
	s_mov_b32 s15, 0
	v_cmp_eq_u32_e32 vcc, 0, v1
	s_waitcnt vmcnt(0)
	s_and_saveexec_b64 s[10:11], vcc
	s_cbranch_execz .LBB0_1057
	s_add_i32 s14, s2, 0x900
	s_lshl_b64 s[4:5], s[14:15], 2
	v_readlane_b32 s2, v228, 8
	s_add_u32 s4, s2, s4
	v_readlane_b32 s2, v228, 10
	s_addc_u32 s5, s2, s5
	s_bcnt1_i32_b64 s2, s[8:9]
	v_mov_b32_e32 v1, 0
	v_mov_b32_e32 v2, s2
	global_atomic_add v1, v2, s[4:5]

.LBB0_1676:
	s_or_b64 exec, exec, s[10:11]
	v_cvt_f32_u32_e32 v5, v3
	s_waitcnt vmcnt(0)
	v_readfirstlane_b32 s4, v4
	v_sub_u32_e32 v4, 0, v3
	v_rcp_iflag_f32_e32 v5, v5
	v_add_u32_e32 v6, s4, v2
	v_mul_f32_e32 v5, 0x4f7ffffe, v5
	v_cvt_u32_f32_e32 v5, v5
	v_mul_lo_u32 v2, v4, v5
	v_mul_hi_u32 v2, v5, v2
	v_add_u32_e32 v2, v5, v2
	v_mul_hi_u32 v2, v6, v2
	v_mul_lo_u32 v4, v2, v3
	v_sub_u32_e32 v4, v6, v4
	v_add_u32_e32 v5, 1, v2
	v_cmp_ge_u32_e32 vcc, v4, v3
	s_nop 1
	v_cndmask_b32_e32 v2, v2, v5, vcc
	v_sub_u32_e32 v5, v4, v3
	v_cndmask_b32_e32 v4, v4, v5, vcc
	v_add_u32_e32 v5, 1, v2
	v_cmp_ge_u32_e32 vcc, v4, v3
	v_add_u32_e32 v4, 1, v6
	s_nop 0
	v_cndmask_b32_e32 v2, v2, v5, vcc
	v_mul_lo_u32 v5, v3, v2
	v_add_u32_e32 v3, v5, v3
	v_cmp_ne_u32_e32 vcc, v4, v3
	s_and_saveexec_b64 s[4:5], vcc
	s_xor_b64 s[8:9], exec, s[4:5]
	s_cbranch_execz .LBB0_1690
	s_add_i32 s4, s2, 0x900
	s_mov_b32 s5, 0
	s_lshl_b64 s[4:5], s[4:5], 2
	v_readlane_b32 s10, v228, 8
	s_add_u32 s14, s10, s4
	v_readlane_b32 s4, v228, 10
	s_addc_u32 s15, s4, s5
	s_waitcnt lgkmcnt(0)
	v_mov_b32_e32 v1, 0
	buffer_inv sc1
	global_load_dword v3, v1, s[14:15] sc1
	s_waitcnt vmcnt(0)
	v_cmp_eq_u32_e32 vcc, v3, v2
	s_and_saveexec_b64 s[10:11], vcc
	s_cbranch_execz .LBB0_1689
	s_add_u32 s12, s38, 0x4200
	s_addc_u32 s13, s39, 0
	s_mov_b32 s4, 1
	s_mov_b64 s[16:17], 0
	s_branch .LBB0_1680

.LBB0_1707:
	s_or_b64 exec, exec, s[8:9]
	s_mov_b64 s[8:9], exec
	v_mbcnt_lo_u32_b32 v1, s8, 0
	v_mbcnt_hi_u32_b32 v1, s9, v1
	s_mov_b32 s13, 0
	v_cmp_eq_u32_e32 vcc, 0, v1
	s_waitcnt vmcnt(0)
	s_and_saveexec_b64 s[10:11], vcc
	s_cbranch_execz .LBB0_1709
	s_add_i32 s12, s2, 0x900
	s_lshl_b64 s[4:5], s[12:13], 2
	v_readlane_b32 s2, v228, 8
	s_add_u32 s4, s2, s4
	v_readlane_b32 s2, v228, 10
	s_addc_u32 s5, s2, s5
	s_bcnt1_i32_b64 s2, s[8:9]
	v_mov_b32_e32 v1, 0
	v_mov_b32_e32 v2, s2
	global_atomic_add v1, v2, s[4:5]

.LBB0_2223:
	s_or_b64 exec, exec, s[10:11]
	v_cvt_f32_u32_e32 v5, v3
	s_waitcnt vmcnt(0)
	v_readfirstlane_b32 s3, v4
	v_sub_u32_e32 v4, 0, v3
	v_rcp_iflag_f32_e32 v5, v5
	v_add_u32_e32 v6, s3, v2
	v_mul_f32_e32 v5, 0x4f7ffffe, v5
	v_cvt_u32_f32_e32 v5, v5
	v_mul_lo_u32 v2, v4, v5
	v_mul_hi_u32 v2, v5, v2
	v_add_u32_e32 v2, v5, v2
	v_mul_hi_u32 v2, v6, v2
	v_mul_lo_u32 v4, v2, v3
	v_sub_u32_e32 v4, v6, v4
	v_add_u32_e32 v5, 1, v2
	v_cmp_ge_u32_e32 vcc, v4, v3
	s_nop 1
	v_cndmask_b32_e32 v2, v2, v5, vcc
	v_sub_u32_e32 v5, v4, v3
	v_cndmask_b32_e32 v4, v4, v5, vcc
	v_add_u32_e32 v5, 1, v2
	v_cmp_ge_u32_e32 vcc, v4, v3
	v_add_u32_e32 v4, 1, v6
	s_nop 0
	v_cndmask_b32_e32 v2, v2, v5, vcc
	v_mul_lo_u32 v5, v3, v2
	v_add_u32_e32 v3, v5, v3
	v_cmp_ne_u32_e32 vcc, v4, v3
	s_and_saveexec_b64 s[4:5], vcc
	s_xor_b64 s[8:9], exec, s[4:5]
	s_cbranch_execz .LBB0_2237
	s_add_i32 s4, s2, 0x900
	s_mov_b32 s5, 0
	s_lshl_b64 s[4:5], s[4:5], 2
	v_readlane_b32 s3, v228, 8
	s_add_u32 s14, s3, s4
	v_readlane_b32 s3, v228, 10
	s_addc_u32 s15, s3, s5
	s_waitcnt lgkmcnt(0)
	v_mov_b32_e32 v1, 0
	buffer_inv sc1
	global_load_dword v3, v1, s[14:15] sc1
	s_waitcnt vmcnt(0)
	v_cmp_eq_u32_e32 vcc, v3, v2
	s_and_saveexec_b64 s[10:11], vcc
	s_cbranch_execz .LBB0_2236
	s_add_u32 s12, s38, 0x4200
	s_addc_u32 s13, s39, 0
	s_mov_b32 s3, 1
	s_mov_b64 s[16:17], 0
	s_branch .LBB0_2227

.LBB0_2237:
	s_andn2_saveexec_b64 s[4:5], s[8:9]
	s_cbranch_execz .LBB0_2257
	s_mov_b64 s[8:9], exec
	buffer_wbl2 sc1
	s_waitcnt lgkmcnt(0)
	s_waitcnt vmcnt(0)
	buffer_inv sc1
	v_mbcnt_lo_u32_b32 v2, s8, 0
	v_mbcnt_hi_u32_b32 v2, s9, v2
	v_cmp_eq_u32_e32 vcc, 0, v2
	s_and_saveexec_b64 s[10:11], vcc
	s_cbranch_execz .LBB0_2240
	s_bcnt1_i32_b64 s3, s[8:9]
	v_mov_b32_e32 v3, 0x7000
	v_mov_b32_e32 v4, s3
	global_atomic_add v3, v3, v4, s[38:39] offset:1024 sc0

.LBB0_2254:
	s_or_b64 exec, exec, s[8:9]
	s_mov_b64 s[8:9], exec
	v_mbcnt_lo_u32_b32 v1, s8, 0
	v_mbcnt_hi_u32_b32 v1, s9, v1
	s_mov_b32 s13, 0
	v_cmp_eq_u32_e32 vcc, 0, v1
	s_waitcnt vmcnt(0)
	s_and_saveexec_b64 s[10:11], vcc
	s_cbranch_execz .LBB0_2256
	s_add_i32 s12, s2, 0x900
	s_lshl_b64 s[2:3], s[12:13], 2
	v_readlane_b32 s4, v228, 8
	s_add_u32 s2, s4, s2
	v_readlane_b32 s4, v228, 10
	s_addc_u32 s3, s4, s3
	s_bcnt1_i32_b64 s4, s[8:9]
	v_mov_b32_e32 v1, 0
	v_mov_b32_e32 v2, s4
	global_atomic_add v1, v2, s[2:3]

.LBB0_2987:
	s_or_b64 exec, exec, s[12:13]
	v_cvt_f32_u32_e32 v5, v3
	s_waitcnt vmcnt(0)
	v_readfirstlane_b32 s3, v4
	v_sub_u32_e32 v4, 0, v3
	v_rcp_iflag_f32_e32 v5, v5
	v_add_u32_e32 v6, s3, v2
	v_mul_f32_e32 v5, 0x4f7ffffe, v5
	v_cvt_u32_f32_e32 v5, v5
	v_mul_lo_u32 v2, v4, v5
	v_mul_hi_u32 v2, v5, v2
	v_add_u32_e32 v2, v5, v2
	v_mul_hi_u32 v2, v6, v2
	v_mul_lo_u32 v4, v2, v3
	v_sub_u32_e32 v4, v6, v4
	v_add_u32_e32 v5, 1, v2
	v_cmp_ge_u32_e32 vcc, v4, v3
	s_nop 1
	v_cndmask_b32_e32 v2, v2, v5, vcc
	v_sub_u32_e32 v5, v4, v3
	v_cndmask_b32_e32 v4, v4, v5, vcc
	v_add_u32_e32 v5, 1, v2
	v_cmp_ge_u32_e32 vcc, v4, v3
	v_add_u32_e32 v4, 1, v6
	s_nop 0
	v_cndmask_b32_e32 v2, v2, v5, vcc
	v_mul_lo_u32 v5, v3, v2
	v_add_u32_e32 v3, v5, v3
	v_cmp_ne_u32_e32 vcc, v4, v3
	s_and_saveexec_b64 s[10:11], vcc
	s_xor_b64 s[10:11], exec, s[10:11]
	s_cbranch_execz .LBB0_3001
	s_add_i32 s12, s2, 0x900
	s_mov_b32 s13, 0
	s_lshl_b64 s[12:13], s[12:13], 2
	v_readlane_b32 s3, v228, 8
	s_add_u32 s16, s3, s12
	v_readlane_b32 s3, v228, 10
	s_addc_u32 s17, s3, s13
	s_waitcnt lgkmcnt(0)
	v_mov_b32_e32 v1, 0
	buffer_inv sc1
	global_load_dword v3, v1, s[16:17] sc1
	s_waitcnt vmcnt(0)
	v_cmp_eq_u32_e32 vcc, v3, v2
	s_and_saveexec_b64 s[12:13], vcc
	s_cbranch_execz .LBB0_3000
	s_add_u32 s14, s38, 0x4200
	s_addc_u32 s15, s39, 0
	s_mov_b32 s3, 1
	s_mov_b64 s[18:19], 0
	s_branch .LBB0_2991

.LBB0_3001:
	s_andn2_saveexec_b64 s[10:11], s[10:11]
	s_cbranch_execz .LBB0_3021
	s_mov_b64 s[10:11], exec
	buffer_wbl2 sc1
	s_waitcnt lgkmcnt(0)
	s_waitcnt vmcnt(0)
	buffer_inv sc1
	v_mbcnt_lo_u32_b32 v2, s10, 0
	v_mbcnt_hi_u32_b32 v2, s11, v2
	v_cmp_eq_u32_e32 vcc, 0, v2
	s_and_saveexec_b64 s[12:13], vcc
	s_cbranch_execz .LBB0_3004
	s_bcnt1_i32_b64 s3, s[10:11]
	v_mov_b32_e32 v3, 0x7000
	v_mov_b32_e32 v4, s3
	global_atomic_add v3, v3, v4, s[38:39] offset:1024 sc0

.LBB0_3018:
	s_or_b64 exec, exec, s[10:11]
	s_mov_b64 s[10:11], exec
	v_mbcnt_lo_u32_b32 v1, s10, 0
	v_mbcnt_hi_u32_b32 v1, s11, v1
	s_mov_b32 s15, 0
	v_cmp_eq_u32_e32 vcc, 0, v1
	s_waitcnt vmcnt(0)
	s_and_saveexec_b64 s[12:13], vcc
	s_cbranch_execz .LBB0_3020
	s_add_i32 s14, s2, 0x900
	s_lshl_b64 s[2:3], s[14:15], 2
	v_readlane_b32 s4, v228, 8
	s_add_u32 s2, s4, s2
	v_readlane_b32 s4, v228, 10
	s_addc_u32 s3, s4, s3
	s_bcnt1_i32_b64 s4, s[10:11]
	v_mov_b32_e32 v1, 0
	v_mov_b32_e32 v2, s4
	global_atomic_add v1, v2, s[2:3]

.LBB0_3238:
	s_or_b64 exec, exec, s[20:21]
	v_cvt_f32_u32_e32 v5, v3
	s_waitcnt vmcnt(0)
	v_readfirstlane_b32 s10, v4
	v_sub_u32_e32 v4, 0, v3
	v_rcp_iflag_f32_e32 v5, v5
	v_add_u32_e32 v6, s10, v2
	v_mul_f32_e32 v5, 0x4f7ffffe, v5
	v_cvt_u32_f32_e32 v5, v5
	v_mul_lo_u32 v2, v4, v5
	v_mul_hi_u32 v2, v5, v2
	v_add_u32_e32 v2, v5, v2
	v_mul_hi_u32 v2, v6, v2
	v_mul_lo_u32 v4, v2, v3
	v_sub_u32_e32 v4, v6, v4
	v_add_u32_e32 v5, 1, v2
	v_cmp_ge_u32_e32 vcc, v4, v3
	s_nop 1
	v_cndmask_b32_e32 v2, v2, v5, vcc
	v_sub_u32_e32 v5, v4, v3
	v_cndmask_b32_e32 v4, v4, v5, vcc
	v_add_u32_e32 v5, 1, v2
	v_cmp_ge_u32_e32 vcc, v4, v3
	v_add_u32_e32 v4, 1, v6
	s_nop 0
	v_cndmask_b32_e32 v2, v2, v5, vcc
	v_mul_lo_u32 v5, v3, v2
	v_add_u32_e32 v3, v5, v3
	v_cmp_ne_u32_e32 vcc, v4, v3
	s_and_saveexec_b64 s[10:11], vcc
	s_xor_b64 s[10:11], exec, s[10:11]
	s_cbranch_execz .LBB0_3252
	s_add_i32 s20, s17, 0x900
	s_mov_b32 s21, 0
	s_lshl_b64 s[20:21], s[20:21], 2
	s_add_u32 s24, s3, s20
	s_addc_u32 s25, s4, s21
	s_waitcnt lgkmcnt(0)
	v_mov_b32_e32 v1, 0
	buffer_inv sc1
	global_load_dword v3, v1, s[24:25] sc1
	s_waitcnt vmcnt(0)
	v_cmp_eq_u32_e32 vcc, v3, v2
	s_and_saveexec_b64 s[20:21], vcc
	s_cbranch_execz .LBB0_3251
	s_add_u32 s22, s12, 0x4200
	s_addc_u32 s23, s13, 0
	s_mov_b32 s28, 1
	s_mov_b64 s[26:27], 0
	s_branch .LBB0_3242

.LBB0_3251:
	s_or_b64 exec, exec, s[20:21]
	s_waitcnt vmcnt(0)
	s_waitcnt vmcnt(0)
.LBB0_3252:
	s_andn2_saveexec_b64 s[10:11], s[10:11]
	s_cbranch_execz .LBB0_3272
	s_mov_b64 s[10:11], exec
	buffer_wbl2 sc1
	s_waitcnt lgkmcnt(0)
	s_waitcnt vmcnt(0)
	buffer_inv sc1
	v_mbcnt_lo_u32_b32 v2, s10, 0
	v_mbcnt_hi_u32_b32 v2, s11, v2
	v_cmp_eq_u32_e32 vcc, 0, v2
	s_and_saveexec_b64 s[20:21], vcc
	s_cbranch_execz .LBB0_3255
	s_bcnt1_i32_b64 s10, s[10:11]
	v_mov_b32_e32 v3, 0x7000
	v_mov_b32_e32 v4, s10
	global_atomic_add v3, v3, v4, s[12:13] offset:1024 sc0

.LBB0_3269:
	s_or_b64 exec, exec, s[10:11]
	s_mov_b64 s[10:11], exec
	v_mbcnt_lo_u32_b32 v1, s10, 0
	v_mbcnt_hi_u32_b32 v1, s11, v1
	s_mov_b32 s23, 0
	v_cmp_eq_u32_e32 vcc, 0, v1
	s_waitcnt vmcnt(0)
	s_and_saveexec_b64 s[20:21], vcc
	s_cbranch_execz .LBB0_3271
	s_add_i32 s22, s17, 0x900
	s_lshl_b64 s[22:23], s[22:23], 2
	s_add_u32 s22, s3, s22
	s_addc_u32 s23, s4, s23
	s_bcnt1_i32_b64 s10, s[10:11]
	v_mov_b32_e32 v1, 0
	v_mov_b32_e32 v2, s10
	global_atomic_add v1, v2, s[22:23]

.LBB0_3361:
	s_or_b64 exec, exec, s[10:11]
	v_cvt_f32_u32_e32 v5, v3
	s_waitcnt vmcnt(0)
	v_readfirstlane_b32 s5, v4
	v_sub_u32_e32 v4, 0, v3
	v_rcp_iflag_f32_e32 v5, v5
	v_add_u32_e32 v6, s5, v2
	v_mul_f32_e32 v5, 0x4f7ffffe, v5
	v_cvt_u32_f32_e32 v5, v5
	v_mul_lo_u32 v2, v4, v5
	v_mul_hi_u32 v2, v5, v2
	v_add_u32_e32 v2, v5, v2
	v_mul_hi_u32 v2, v6, v2
	v_mul_lo_u32 v4, v2, v3
	v_sub_u32_e32 v4, v6, v4
	v_add_u32_e32 v5, 1, v2
	v_cmp_ge_u32_e32 vcc, v4, v3
	s_nop 1
	v_cndmask_b32_e32 v2, v2, v5, vcc
	v_sub_u32_e32 v5, v4, v3
	v_cndmask_b32_e32 v4, v4, v5, vcc
	v_add_u32_e32 v5, 1, v2
	v_cmp_ge_u32_e32 vcc, v4, v3
	v_add_u32_e32 v4, 1, v6
	s_nop 0
	v_cndmask_b32_e32 v2, v2, v5, vcc
	v_mul_lo_u32 v5, v3, v2
	v_add_u32_e32 v3, v5, v3
	v_cmp_ne_u32_e32 vcc, v4, v3
	s_and_saveexec_b64 s[8:9], vcc
	s_xor_b64 s[8:9], exec, s[8:9]
	s_cbranch_execz .LBB0_3375
	s_add_i32 s10, s2, 0x900
	s_mov_b32 s11, 0
	s_lshl_b64 s[10:11], s[10:11], 2
	s_add_u32 s16, s3, s10
	s_addc_u32 s17, s4, s11
	s_waitcnt lgkmcnt(0)
	v_mov_b32_e32 v1, 0
	buffer_inv sc1
	global_load_dword v3, v1, s[16:17] sc1
	s_waitcnt vmcnt(0)
	v_cmp_eq_u32_e32 vcc, v3, v2
	s_and_saveexec_b64 s[10:11], vcc
	s_cbranch_execz .LBB0_3374
	s_add_u32 s14, s12, 0x4200
	s_addc_u32 s15, s13, 0
	s_mov_b32 s5, 1
	s_mov_b64 s[18:19], 0
	s_branch .LBB0_3365

.LBB0_3375:
	s_andn2_saveexec_b64 s[8:9], s[8:9]
	s_cbranch_execz .LBB0_3395
	s_mov_b64 s[8:9], exec
	buffer_wbl2 sc1
	s_waitcnt lgkmcnt(0)
	s_waitcnt vmcnt(0)
	buffer_inv sc1
	v_mbcnt_lo_u32_b32 v2, s8, 0
	v_mbcnt_hi_u32_b32 v2, s9, v2
	v_cmp_eq_u32_e32 vcc, 0, v2
	s_and_saveexec_b64 s[10:11], vcc
	s_cbranch_execz .LBB0_3378
	s_bcnt1_i32_b64 s5, s[8:9]
	v_mov_b32_e32 v3, 0x7000
	v_mov_b32_e32 v4, s5
	global_atomic_add v3, v3, v4, s[12:13] offset:1024 sc0

.LBB0_3392:
	s_or_b64 exec, exec, s[8:9]
	s_mov_b64 s[8:9], exec
	v_mbcnt_lo_u32_b32 v1, s8, 0
	v_mbcnt_hi_u32_b32 v1, s9, v1
	s_mov_b32 s13, 0
	v_cmp_eq_u32_e32 vcc, 0, v1
	s_waitcnt vmcnt(0)
	s_and_saveexec_b64 s[10:11], vcc
	s_cbranch_execz .LBB0_3394
	s_add_i32 s12, s2, 0x900
	s_lshl_b64 s[12:13], s[12:13], 2
	s_add_u32 s2, s3, s12
	s_addc_u32 s3, s4, s13
	s_bcnt1_i32_b64 s4, s[8:9]
	v_mov_b32_e32 v1, 0
	v_mov_b32_e32 v2, s4
	global_atomic_add v1, v2, s[2:3]

.LBB0_3508:
	s_or_b64 exec, exec, s[16:17]
	v_cvt_f32_u32_e32 v5, v3
	s_waitcnt vmcnt(0)
	v_readfirstlane_b32 s4, v4
	v_sub_u32_e32 v4, 0, v3
	v_rcp_iflag_f32_e32 v5, v5
	v_add_u32_e32 v6, s4, v2
	v_mul_f32_e32 v5, 0x4f7ffffe, v5
	v_cvt_u32_f32_e32 v5, v5
	v_mul_lo_u32 v2, v4, v5
	v_mul_hi_u32 v2, v5, v2
	v_add_u32_e32 v2, v5, v2
	v_mul_hi_u32 v2, v6, v2
	v_mul_lo_u32 v4, v2, v3
	v_sub_u32_e32 v4, v6, v4
	v_add_u32_e32 v5, 1, v2
	v_cmp_ge_u32_e32 vcc, v4, v3
	s_nop 1
	v_cndmask_b32_e32 v2, v2, v5, vcc
	v_sub_u32_e32 v5, v4, v3
	v_cndmask_b32_e32 v4, v4, v5, vcc
	v_add_u32_e32 v5, 1, v2
	v_cmp_ge_u32_e32 vcc, v4, v3
	v_add_u32_e32 v4, 1, v6
	s_nop 0
	v_cndmask_b32_e32 v2, v2, v5, vcc
	v_mul_lo_u32 v5, v3, v2
	v_add_u32_e32 v3, v5, v3
	v_cmp_ne_u32_e32 vcc, v4, v3
	s_and_saveexec_b64 s[4:5], vcc
	s_xor_b64 s[10:11], exec, s[4:5]
	s_cbranch_execz .LBB0_3522
	s_add_i32 s4, s3, 0x900
	s_mov_b32 s5, 0
	s_lshl_b64 s[4:5], s[4:5], 2
	v_readlane_b32 s13, v228, 19
	s_add_u32 s20, s13, s4
	v_readlane_b32 s4, v228, 23
	s_addc_u32 s21, s4, s5
	s_waitcnt lgkmcnt(0)
	v_mov_b32_e32 v1, 0
	buffer_inv sc1
	global_load_dword v3, v1, s[20:21] sc1
	s_waitcnt vmcnt(0)
	v_cmp_eq_u32_e32 vcc, v3, v2
	s_and_saveexec_b64 s[16:17], vcc
	s_cbranch_execz .LBB0_3521
	s_add_u32 s18, s38, 0x4200
	s_addc_u32 s19, s39, 0
	s_mov_b32 s4, 1
	s_mov_b64 s[22:23], 0
	s_branch .LBB0_3512

.LBB0_3521:
	s_or_b64 exec, exec, s[16:17]
	s_waitcnt vmcnt(0)
	s_waitcnt vmcnt(0)
.LBB0_3522:
	s_andn2_saveexec_b64 s[4:5], s[10:11]
	s_cbranch_execz .LBB0_3542
	s_mov_b64 s[10:11], exec
	buffer_wbl2 sc1
	s_waitcnt lgkmcnt(0)
	s_waitcnt vmcnt(0)
	buffer_inv sc1
	v_mbcnt_lo_u32_b32 v2, s10, 0
	v_mbcnt_hi_u32_b32 v2, s11, v2
	v_cmp_eq_u32_e32 vcc, 0, v2
	s_and_saveexec_b64 s[16:17], vcc
	s_cbranch_execz .LBB0_3525
	s_bcnt1_i32_b64 s4, s[10:11]
	v_mov_b32_e32 v3, 0x7000
	v_mov_b32_e32 v4, s4
	global_atomic_add v3, v3, v4, s[38:39] offset:1024 sc0

.LBB0_3539:
	s_or_b64 exec, exec, s[10:11]
	s_mov_b64 s[10:11], exec
	v_mbcnt_lo_u32_b32 v1, s10, 0
	v_mbcnt_hi_u32_b32 v1, s11, v1
	s_mov_b32 s19, 0
	v_cmp_eq_u32_e32 vcc, 0, v1
	s_waitcnt vmcnt(0)
	s_and_saveexec_b64 s[16:17], vcc
	s_cbranch_execz .LBB0_3541
	s_add_i32 s18, s3, 0x900
	s_lshl_b64 s[4:5], s[18:19], 2
	v_readlane_b32 s3, v228, 19
	s_add_u32 s4, s3, s4
	v_readlane_b32 s3, v228, 23
	s_addc_u32 s5, s3, s5
	s_bcnt1_i32_b64 s3, s[10:11]
	v_mov_b32_e32 v1, 0
	v_mov_b32_e32 v2, s3
	global_atomic_add v1, v2, s[4:5]

.LBB0_3631:
	s_or_b64 exec, exec, s[10:11]
	v_cvt_f32_u32_e32 v5, v3
	s_waitcnt vmcnt(0)
	v_readfirstlane_b32 s3, v4
	v_sub_u32_e32 v4, 0, v3
	v_rcp_iflag_f32_e32 v5, v5
	v_add_u32_e32 v6, s3, v2
	v_mul_f32_e32 v5, 0x4f7ffffe, v5
	v_cvt_u32_f32_e32 v5, v5
	v_mul_lo_u32 v2, v4, v5
	v_mul_hi_u32 v2, v5, v2
	v_add_u32_e32 v2, v5, v2
	v_mul_hi_u32 v2, v6, v2
	v_mul_lo_u32 v4, v2, v3
	v_sub_u32_e32 v4, v6, v4
	v_add_u32_e32 v5, 1, v2
	v_cmp_ge_u32_e32 vcc, v4, v3
	s_nop 1
	v_cndmask_b32_e32 v2, v2, v5, vcc
	v_sub_u32_e32 v5, v4, v3
	v_cndmask_b32_e32 v4, v4, v5, vcc
	v_add_u32_e32 v5, 1, v2
	v_cmp_ge_u32_e32 vcc, v4, v3
	v_add_u32_e32 v4, 1, v6
	s_nop 0
	v_cndmask_b32_e32 v2, v2, v5, vcc
	v_mul_lo_u32 v5, v3, v2
	v_add_u32_e32 v3, v5, v3
	v_cmp_ne_u32_e32 vcc, v4, v3
	s_and_saveexec_b64 s[4:5], vcc
	s_xor_b64 s[8:9], exec, s[4:5]
	s_cbranch_execz .LBB0_3645
	s_add_i32 s4, s2, 0x900
	s_mov_b32 s5, 0
	s_lshl_b64 s[4:5], s[4:5], 2
	v_readlane_b32 s3, v228, 19
	s_add_u32 s16, s3, s4
	v_readlane_b32 s3, v228, 23
	s_addc_u32 s17, s3, s5
	s_waitcnt lgkmcnt(0)
	v_mov_b32_e32 v1, 0
	buffer_inv sc1
	global_load_dword v3, v1, s[16:17] sc1
	s_waitcnt vmcnt(0)
	v_cmp_eq_u32_e32 vcc, v3, v2
	s_and_saveexec_b64 s[10:11], vcc
	s_cbranch_execz .LBB0_3644
	s_add_u32 s14, s38, 0x4200
	s_addc_u32 s15, s39, 0
	s_mov_b32 s3, 1
	s_mov_b64 s[18:19], 0
	s_branch .LBB0_3635

.LBB0_3662:
	s_or_b64 exec, exec, s[8:9]
	s_mov_b64 s[8:9], exec
	v_mbcnt_lo_u32_b32 v1, s8, 0
	v_mbcnt_hi_u32_b32 v1, s9, v1
	s_mov_b32 s15, 0
	v_cmp_eq_u32_e32 vcc, 0, v1
	s_waitcnt vmcnt(0)
	s_and_saveexec_b64 s[10:11], vcc
	s_cbranch_execz .LBB0_3664
	s_add_i32 s14, s2, 0x900
	s_lshl_b64 s[2:3], s[14:15], 2
	v_readlane_b32 s4, v228, 19
	s_add_u32 s2, s4, s2
	v_readlane_b32 s4, v228, 23
	s_addc_u32 s3, s4, s3
	s_bcnt1_i32_b64 s4, s[8:9]
	v_mov_b32_e32 v1, 0
	v_mov_b32_e32 v2, s4
	global_atomic_add v1, v2, s[2:3]

.LBB0_4283:
	s_or_b64 exec, exec, s[10:11]
	v_cvt_f32_u32_e32 v5, v3
	s_waitcnt vmcnt(0)
	v_readfirstlane_b32 s3, v4
	v_sub_u32_e32 v4, 0, v3
	v_rcp_iflag_f32_e32 v5, v5
	v_add_u32_e32 v6, s3, v2
	v_mul_f32_e32 v5, 0x4f7ffffe, v5
	v_cvt_u32_f32_e32 v5, v5
	v_mul_lo_u32 v2, v4, v5
	v_mul_hi_u32 v2, v5, v2
	v_add_u32_e32 v2, v5, v2
	v_mul_hi_u32 v2, v6, v2
	v_mul_lo_u32 v4, v2, v3
	v_sub_u32_e32 v4, v6, v4
	v_add_u32_e32 v5, 1, v2
	v_cmp_ge_u32_e32 vcc, v4, v3
	s_nop 1
	v_cndmask_b32_e32 v2, v2, v5, vcc
	v_sub_u32_e32 v5, v4, v3
	v_cndmask_b32_e32 v4, v4, v5, vcc
	v_add_u32_e32 v5, 1, v2
	v_cmp_ge_u32_e32 vcc, v4, v3
	v_add_u32_e32 v4, 1, v6
	s_nop 0
	v_cndmask_b32_e32 v2, v2, v5, vcc
	v_mul_lo_u32 v5, v3, v2
	v_add_u32_e32 v3, v5, v3
	v_cmp_ne_u32_e32 vcc, v4, v3
	s_and_saveexec_b64 s[4:5], vcc
	s_xor_b64 s[8:9], exec, s[4:5]
	s_cbranch_execz .LBB0_4297
	s_add_i32 s4, s2, 0x900
	s_mov_b32 s5, 0
	s_lshl_b64 s[4:5], s[4:5], 2
	v_readlane_b32 s3, v228, 19
	s_add_u32 s14, s3, s4
	v_readlane_b32 s3, v228, 23
	s_addc_u32 s15, s3, s5
	s_waitcnt lgkmcnt(0)
	v_mov_b32_e32 v1, 0
	buffer_inv sc1
	global_load_dword v3, v1, s[14:15] sc1
	s_waitcnt vmcnt(0)
	v_cmp_eq_u32_e32 vcc, v3, v2
	s_and_saveexec_b64 s[10:11], vcc
	s_cbranch_execz .LBB0_4296
	s_add_u32 s12, s38, 0x4200
	s_addc_u32 s13, s39, 0
	s_mov_b32 s3, 1
	s_mov_b64 s[16:17], 0
	s_branch .LBB0_4287

.LBB0_4314:
	s_or_b64 exec, exec, s[8:9]
	s_mov_b64 s[8:9], exec
	v_mbcnt_lo_u32_b32 v1, s8, 0
	v_mbcnt_hi_u32_b32 v1, s9, v1
	s_mov_b32 s13, 0
	v_cmp_eq_u32_e32 vcc, 0, v1
	s_waitcnt vmcnt(0)
	s_and_saveexec_b64 s[10:11], vcc
	s_cbranch_execz .LBB0_4316
	s_add_i32 s12, s2, 0x900
	s_lshl_b64 s[2:3], s[12:13], 2
	v_readlane_b32 s4, v228, 19
	s_add_u32 s2, s4, s2
	v_readlane_b32 s4, v228, 23
	s_addc_u32 s3, s4, s3
	s_bcnt1_i32_b64 s4, s[8:9]
	v_mov_b32_e32 v1, 0
	v_mov_b32_e32 v2, s4
	global_atomic_add v1, v2, s[2:3]

.LBB0_5594:
	s_or_b64 exec, exec, s[12:13]
	v_cvt_f32_u32_e32 v5, v3
	s_waitcnt vmcnt(0)
	v_readfirstlane_b32 s3, v4
	v_sub_u32_e32 v4, 0, v3
	v_rcp_iflag_f32_e32 v5, v5
	v_add_u32_e32 v6, s3, v2
	v_mul_f32_e32 v5, 0x4f7ffffe, v5
	v_cvt_u32_f32_e32 v5, v5
	v_mul_lo_u32 v2, v4, v5
	v_mul_hi_u32 v2, v5, v2
	v_add_u32_e32 v2, v5, v2
	v_mul_hi_u32 v2, v6, v2
	v_mul_lo_u32 v4, v2, v3
	v_sub_u32_e32 v4, v6, v4
	v_add_u32_e32 v5, 1, v2
	v_cmp_ge_u32_e32 vcc, v4, v3
	s_nop 1
	v_cndmask_b32_e32 v2, v2, v5, vcc
	v_sub_u32_e32 v5, v4, v3
	v_cndmask_b32_e32 v4, v4, v5, vcc
	v_add_u32_e32 v5, 1, v2
	v_cmp_ge_u32_e32 vcc, v4, v3
	v_add_u32_e32 v4, 1, v6
	s_nop 0
	v_cndmask_b32_e32 v2, v2, v5, vcc
	v_mul_lo_u32 v5, v3, v2
	v_add_u32_e32 v3, v5, v3
	v_cmp_ne_u32_e32 vcc, v4, v3
	s_and_saveexec_b64 s[10:11], vcc
	s_xor_b64 s[10:11], exec, s[10:11]
	s_cbranch_execz .LBB0_5608
	s_add_i32 s12, s2, 0x900
	s_mov_b32 s13, 0
	s_lshl_b64 s[12:13], s[12:13], 2
	v_readlane_b32 s3, v228, 19
	s_add_u32 s16, s3, s12
	v_readlane_b32 s3, v228, 23
	s_addc_u32 s17, s3, s13
	s_waitcnt lgkmcnt(0)
	v_mov_b32_e32 v1, 0
	buffer_inv sc1
	global_load_dword v3, v1, s[16:17] sc1
	s_waitcnt vmcnt(0)
	v_cmp_eq_u32_e32 vcc, v3, v2
	s_and_saveexec_b64 s[12:13], vcc
	s_cbranch_execz .LBB0_5607
	s_add_u32 s14, s38, 0x4200
	s_addc_u32 s15, s39, 0
	s_mov_b32 s3, 1
	s_mov_b64 s[18:19], 0
	s_branch .LBB0_5598

.LBB0_5625:
	s_or_b64 exec, exec, s[10:11]
	s_mov_b64 s[10:11], exec
	v_mbcnt_lo_u32_b32 v1, s10, 0
	v_mbcnt_hi_u32_b32 v1, s11, v1
	s_mov_b32 s15, 0
	v_cmp_eq_u32_e32 vcc, 0, v1
	s_waitcnt vmcnt(0)
	s_and_saveexec_b64 s[12:13], vcc
	s_cbranch_execz .LBB0_5627
	s_add_i32 s14, s2, 0x900
	s_lshl_b64 s[2:3], s[14:15], 2
	v_readlane_b32 s4, v228, 19
	s_add_u32 s2, s4, s2
	v_readlane_b32 s4, v228, 23
	s_addc_u32 s3, s4, s3
	s_bcnt1_i32_b64 s4, s[10:11]
	v_mov_b32_e32 v1, 0
	v_mov_b32_e32 v2, s4
	global_atomic_add v1, v2, s[2:3]

.LBB0_5845:
	s_or_b64 exec, exec, s[12:13]
	v_cvt_f32_u32_e32 v5, v3
	s_waitcnt vmcnt(0)
	v_readfirstlane_b32 s10, v4
	v_sub_u32_e32 v4, 0, v3
	v_rcp_iflag_f32_e32 v5, v5
	v_add_u32_e32 v6, s10, v2
	v_mul_f32_e32 v5, 0x4f7ffffe, v5
	v_cvt_u32_f32_e32 v5, v5
	v_mul_lo_u32 v2, v4, v5
	v_mul_hi_u32 v2, v5, v2
	v_add_u32_e32 v2, v5, v2
	v_mul_hi_u32 v2, v6, v2
	v_mul_lo_u32 v4, v2, v3
	v_sub_u32_e32 v4, v6, v4
	v_add_u32_e32 v5, 1, v2
	v_cmp_ge_u32_e32 vcc, v4, v3
	s_nop 1
	v_cndmask_b32_e32 v2, v2, v5, vcc
	v_sub_u32_e32 v5, v4, v3
	v_cndmask_b32_e32 v4, v4, v5, vcc
	v_add_u32_e32 v5, 1, v2
	v_cmp_ge_u32_e32 vcc, v4, v3
	v_add_u32_e32 v4, 1, v6
	s_nop 0
	v_cndmask_b32_e32 v2, v2, v5, vcc
	v_mul_lo_u32 v5, v3, v2
	v_add_u32_e32 v3, v5, v3
	v_cmp_ne_u32_e32 vcc, v4, v3
	s_and_saveexec_b64 s[10:11], vcc
	s_xor_b64 s[10:11], exec, s[10:11]
	s_cbranch_execz .LBB0_5859
	s_add_i32 s12, s5, 0x900
	s_mov_b32 s13, 0
	s_lshl_b64 s[12:13], s[12:13], 2
	s_add_u32 s18, s3, s12
	s_addc_u32 s19, s4, s13
	s_waitcnt lgkmcnt(0)
	v_mov_b32_e32 v1, 0
	buffer_inv sc1
	global_load_dword v3, v1, s[18:19] sc1
	s_waitcnt vmcnt(0)
	v_cmp_eq_u32_e32 vcc, v3, v2
	s_and_saveexec_b64 s[12:13], vcc
	s_cbranch_execz .LBB0_5858
	s_add_u32 s16, s70, 0x4200
	s_addc_u32 s17, s71, 0
	s_mov_b32 s28, 1
	s_mov_b64 s[20:21], 0
	s_branch .LBB0_5849

.LBB0_5859:
	s_andn2_saveexec_b64 s[10:11], s[10:11]
	s_cbranch_execz .LBB0_5879
	s_mov_b64 s[10:11], exec
	buffer_wbl2 sc1
	s_waitcnt lgkmcnt(0)
	s_waitcnt vmcnt(0)
	buffer_inv sc1
	v_mbcnt_lo_u32_b32 v2, s10, 0
	v_mbcnt_hi_u32_b32 v2, s11, v2
	v_cmp_eq_u32_e32 vcc, 0, v2
	s_and_saveexec_b64 s[12:13], vcc
	s_cbranch_execz .LBB0_5862
	s_bcnt1_i32_b64 s10, s[10:11]
	v_mov_b32_e32 v3, 0x7000
	v_mov_b32_e32 v4, s10
	global_atomic_add v3, v3, v4, s[70:71] offset:1024 sc0

.LBB0_5876:
	s_or_b64 exec, exec, s[10:11]
	s_mov_b64 s[10:11], exec
	v_mbcnt_lo_u32_b32 v1, s10, 0
	v_mbcnt_hi_u32_b32 v1, s11, v1
	s_mov_b32 s17, 0
	v_cmp_eq_u32_e32 vcc, 0, v1
	s_waitcnt vmcnt(0)
	s_and_saveexec_b64 s[12:13], vcc
	s_cbranch_execz .LBB0_5878
	s_add_i32 s16, s5, 0x900
	s_lshl_b64 s[16:17], s[16:17], 2
	s_add_u32 s16, s3, s16
	s_addc_u32 s17, s4, s17
	s_bcnt1_i32_b64 s3, s[10:11]
	v_mov_b32_e32 v1, 0
	v_mov_b32_e32 v2, s3
	global_atomic_add v1, v2, s[16:17]
